# P10 FfnUp epilogue hand-written with packed f32 ops (370 vs 736 instructions); rope inv-frequency chain hoisted out of the table loop in P0
# speedup vs baseline: 1.0176x; 1.0003x over previous
; DI void prologue_rows(const float* const* in, unsigned char* ws, bf16* xb  , int gw, int NGW, int lane) {
;     ...
;     const int* pos = (const int*)in[I_POS]; float* rc = (float*)(ws + WS_RCOS); float* rsn = (float*)(ws + WS_RSIN);
;     for (int e = gw * 64 + lane; e < M * 64; e += NGW * 64) {
;         const int m = e >> 6, i = e & 63; double inv = 1.0; for (int j = 0; j < i; ++j) inv *= 0.8659643233600653523;
;         const double ang = (double)pos[m] * inv;
.LBB0_199:
	v_lshl_add_u32 v0, s74, 6, v64
	s_waitcnt lgkmcnt(0)
	s_mov_b32 s0, 0x100000
	v_cmp_gt_i32_e32 vcc, s0, v0
	s_and_saveexec_b64 s[4:5], vcc
	s_cbranch_execz .LBB0_212
	v_readlane_b32 s0, v254, 7
	v_readlane_b32 s1, v254, 8
	s_load_dwordx2 s[0:1], s[0:1], 0x108
	v_and_b32_e32 v1, 63, v64
	s_mov_b32 s20, 0xd00ab22c
	s_mov_b32 s22, 0x6dc9c883
	s_mov_b32 s24, 0x54442d18
	s_waitcnt lgkmcnt(0)
	s_add_u32 s8, s0, 0x400000
	s_addc_u32 s9, s1, 0
	s_add_u32 s14, s0, 0x800000
	v_readlane_b32 s0, v254, 9
	s_mov_b32 s26, 0x33145c07
	s_mov_b32 s28, 0x13a86d09
	v_mov_b32_e32 v6, 0x1a01a01a
	v_mov_b32_e32 v10, 0x55555555
	s_mov_b32 s30, 0xa8c07c9d
	s_addc_u32 s15, s1, 0
	s_lshl_b32 s6, s0, 9
	v_cmp_ne_u32_e32 vcc, 0, v1
	s_mov_b64 s[18:19], 0
	s_mov_b32 s21, 0x3febb5fa
	s_mov_b32 s23, 0x3fe45f30
	s_movk_i32 s7, 0xffe0
	s_mov_b32 s25, 0xbff921fb
	s_mov_b32 s27, 0xbc91a626
	v_mov_b32_e32 v2, 0x67f544e4
	v_mov_b32_e32 v3, 0xbe5ae645
	s_mov_b32 s29, 0x3de61246
	v_mov_b32_e32 v4, 0xa556c734
	v_mov_b32_e32 v5, 0x3ec71de3
	v_mov_b32_e32 v7, 0xbf2a01a0
	v_mov_b32_e32 v8, 0x11111111
	v_mov_b32_e32 v9, 0x3f811111
	v_mov_b32_e32 v11, 0xbfc55555
	v_mov_b32_e32 v12, 0xeff8d898
	v_mov_b32_e32 v13, 0x3e21eed8
	s_mov_b32 s31, 0xbda93974
	v_mov_b32_e32 v14, 0xb7789f5c
	v_mov_b32_e32 v15, 0xbe927e4f
	v_mov_b32_e32 v17, 0x3efa01a0
	v_mov_b32_e32 v16, v6
	v_mov_b32_e32 v18, 0x16c16c17
	v_mov_b32_e32 v19, 0xbf56c16c
	v_mov_b32_e32 v21, 0x3fa55555
	v_mov_b32_e32 v20, v10
	s_mov_b32 s33, 0xfffff
	v_mov_b32_e32 v22, v0
	v_mov_b64_e32 v[32:33], 1.0
	s_and_saveexec_b64 s[2:3], vcc
	s_cbranch_execz .Lrope_inv_done
	s_mov_b64 s[34:35], 0
	v_mov_b32_e32 v23, v1
.Lrope_inv_loop:
	v_add_u32_e32 v23, -1, v23
	v_cmp_eq_u32_e64 s[0:1], 0, v23
	s_or_b64 s[34:35], s[0:1], s[34:35]
	v_mul_f64 v[32:33], v[32:33], s[20:21]
	s_andn2_b64 exec, exec, s[34:35]
	s_cbranch_execnz .Lrope_inv_loop
	s_or_b64 exec, exec, s[34:35]
.Lrope_inv_done:
	s_or_b64 exec, exec, s[2:3]
	s_branch .LBB0_203

; DI void prologue_rows(const float* const* in, unsigned char* ws, bf16* xb  , int gw, int NGW, int lane) {
;     ...
;     for (int e = gw * 64 + lane; e < M * 64; e += NGW * 64) {
;         const int m = e >> 6, i = e & 63; double inv = 1.0; for (int j = 0; j < i; ++j) inv *= 0.8659643233600653523;
;         const double ang = (double)pos[m] * inv;
;         const double qd = __builtin_rint(ang * 0.63661977236758134308); const int qi = (int)((long long)qd & 3);
;         double r = __builtin_fma(-qd, 1.5707963267948965580, ang); r = __builtin_fma(-qd, 6.1232339957367658860e-17, r);
;         const double r2 = r * r;
;         const double sn = r * (1.0 + r2 * (-1.0 / 6 + r2 * (1.0 / 120 + r2 * (-1.0 / 5040 + r2 * (1.0 / 362880 + r2 * (-1.0 / 39916800 + r2 * (1.0 / 6227020800.0)))))));
;         const double cs = 1.0 + r2 * (-0.5 + r2 * (1.0 / 24 + r2 * (-1.0 / 720 + r2 * (1.0 / 40320 + r2 * (-1.0 / 3628800 + r2 * (1.0 / 479001600.0 + r2 * (-1.0 / 87178291200.0)))))));
;         const double c4 = (qi == 0) ? cs : (qi == 1) ? -sn : (qi == 2) ? -cs : sn;
;         const double s4 = (qi == 0) ? sn : (qi == 1) ? cs : (qi == 2) ? -sn : -cs;
.LBB0_203:
	v_mov_b64_e32 v[24:25], v[32:33]
	v_ashrrev_i32_e32 v26, 6, v22
	v_ashrrev_i32_e32 v27, 31, v26
	v_lshl_add_u64 v[26:27], v[26:27], 2, s[12:13]
	global_load_dword v23, v[26:27], off
	s_waitcnt vmcnt(0)
	v_cvt_f64_i32_e32 v[26:27], v23
	v_mul_f64 v[24:25], v[24:25], v[26:27]
	v_mul_f64 v[26:27], v[24:25], s[22:23]
	v_rndne_f64_e32 v[26:27], v[26:27]
	v_ldexp_f64 v[28:29], v[26:27], s7
	v_fmac_f64_e32 v[24:25], s[24:25], v[26:27]
	v_mov_b64_e32 v[30:31], v[26:27]
	v_floor_f64_e32 v[28:29], v[28:29]
	v_fmac_f64_e32 v[24:25], s[26:27], v[26:27]
	v_fmac_f64_e32 v[30:31], 0xc1f00000, v[28:29]
	v_mul_f64 v[26:27], v[24:25], v[24:25]
	v_cvt_u32_f64_e32 v23, v[30:31]
	v_fma_f64 v[30:31], s[30:31], v[26:27], v[12:13]
	v_fma_f64 v[28:29], s[28:29], v[26:27], v[2:3]
	v_fma_f64 v[30:31], v[26:27], v[30:31], v[14:15]
	v_fma_f64 v[28:29], v[26:27], v[28:29], v[4:5]
	v_fma_f64 v[30:31], v[26:27], v[30:31], v[16:17]
	v_fma_f64 v[28:29], v[26:27], v[28:29], v[6:7]
	v_fma_f64 v[30:31], v[26:27], v[30:31], v[18:19]
	v_fma_f64 v[28:29], v[26:27], v[28:29], v[8:9]
	v_fma_f64 v[30:31], v[26:27], v[30:31], v[20:21]
	v_fma_f64 v[28:29], v[26:27], v[28:29], v[10:11]
	v_fma_f64 v[30:31], v[26:27], v[30:31], -0.5
	v_and_b32_e32 v23, 3, v23
	v_fma_f64 v[28:29], v[26:27], v[28:29], 1.0
	v_fma_f64 v[26:27], v[26:27], v[30:31], 1.0
	v_cmp_eq_u32_e64 s[0:1], 0, v23
	v_mul_f64 v[24:25], v[24:25], v[28:29]
	v_cmp_ne_u32_e64 s[2:3], 0, v23
	v_mov_b64_e32 v[28:29], v[26:27]
	s_and_saveexec_b64 s[34:35], s[2:3]
	s_cbranch_execz .LBB0_202
	v_cmp_ne_u32_e64 s[2:3], 1, v23
	v_xor_b32_e32 v29, 0x80000000, v25
	v_mov_b32_e32 v28, v24
	s_and_saveexec_b64 s[36:37], s[2:3]
	s_xor_b64 s[36:37], exec, s[36:37]
	s_cbranch_execz .LBB0_201
	v_xor_b32_e32 v28, 0x80000000, v27
	v_cmp_eq_u32_e64 s[2:3], 2, v23
	s_nop 1
	v_cndmask_b32_e64 v29, v25, v28, s[2:3]
	v_cndmask_b32_e64 v28, v24, v26, s[2:3]
	s_branch .LBB0_201

; __device__ __forceinline__ int lane_opaque() { int l; asm volatile("v_mbcnt_lo_u32_b32 %0, -1, 0\n\tv_mbcnt_hi_u32_b32 %0, -1, %0" : "=v"(l)); return l; }
; DI float sigmoidf_(float z) { return 1.0f / (1.0f + __expf(-z)); }
; DI v4u pack8(const f4& a, const f4& b) { v4u w; w.x = cvt_pk_bf16(a[0], a[1]); w.y = cvt_pk_bf16(a[2], a[3]); w.z = cvt_pk_bf16(b[0], b[1]); w.w = cvt_pk_bf16(b[2], b[3]); return w; }
;     DI void operator()(f4 (&acc)[2][2][4][2], const Unit& u, int wr, int wc, int fr, int fq) const {
;         { const int ln_ = lane_opaque(); fr = ln_ & 15; fq = ln_ >> 4; }
;         const int row0 = u.pm * BM + wr * 64 + fr, col0 = u.pn * HALF + wc * 32 + 8 * fq;
;         float rr[2][4];
; #pragma unroll
;         for (int ai = 0; ai < 2; ++ai)
; #pragma unroll
;             for (int m = 0; m < 4; ++m) rr[ai][m] = ss[row0 + ai * HALF + m * 16];
; #pragma unroll
;         for (int ai = 0; ai < 2; ++ai)
; #pragma unroll
;             for (int m = 0; m < 4; ++m) { const int row = row0 + ai * HALF + m * 16; const float r = __builtin_amdgcn_rsqf(rr[ai][m] * (1.0f / D) + RMS_EPS);
;                 f4 o0, o1;
; #pragma unroll
;                 for (int e = 0; e < 4; ++e) { const float a0 = acc[ai][0][m][0][e] * r, a1 = acc[ai][0][m][1][e] * r;
;                     o0[e] = a0 * sigmoidf_(a0) * (acc[ai][1][m][0][e] * r); o1[e] = a1 * sigmoidf_(a1) * (acc[ai][1][m][1][e] * r); }
;                 *(v4u*)(uout + (size_t)row * DFF + col0) = pack8(o0, o1); }
.LBB0_2813:
	s_lshl_b32 s0, s0, 8
	s_add_i32 s0, s0, s36
	v_mbcnt_lo_u32_b32 v144, -1, 0
	v_mbcnt_hi_u32_b32 v144, -1, v144
	v_and_or_b32 v148, v144, 15, s0
	v_ashrrev_i32_e32 v149, 31, v148
	v_lshl_add_u64 v[146:147], v[148:149], 2, s[10:11]
	global_load_dword v155, v[146:147], off
	global_load_dword v156, v[146:147], off offset:64
	global_load_dword v157, v[146:147], off offset:128
	global_load_dword v158, v[146:147], off offset:192
	global_load_dword v159, v[146:147], off offset:512
	global_load_dword v160, v[146:147], off offset:576
	global_load_dword v161, v[146:147], off offset:640
	global_load_dword v162, v[146:147], off offset:704
	s_lshl_b32 s0, s1, 7
	s_or_b32 s0, s0, s37
	v_ashrrev_i32_e32 v145, 1, v144
	v_and_b32_e32 v145, -8, v145
	v_add_u32_e32 v164, s0, v145
	v_ashrrev_i32_e32 v165, 31, v164
	v_lshlrev_b64 v[164:165], 1, v[164:165]
	v_lshl_add_u64 v[164:165], v[164:165], 0, s[14:15]
	s_waitcnt vmcnt(0)
	v_fmamk_f32 v166, v155, 0x39800000, v154
	v_rsq_f32_e32 v167, v166
	v_pk_mul_f32 v[120:121], v[124:125], v[120:121]
	v_pk_mul_f32 v[122:123], v[126:127], v[122:123]
	v_pk_mul_f32 v[112:113], v[116:117], v[112:113]
	v_pk_mul_f32 v[114:115], v[118:119], v[114:115]
	v_mul_f32_e32 v168, 0xbfb8aa3b, v167
	v_mov_b32_e32 v149, v148
	v_pk_mul_f32 v[124:125], v[124:125], v[168:169] op_sel_hi:[1,0]
	v_pk_mul_f32 v[126:127], v[126:127], v[168:169] op_sel_hi:[1,0]
	v_pk_mul_f32 v[116:117], v[116:117], v[168:169] op_sel_hi:[1,0]
	v_pk_mul_f32 v[118:119], v[118:119], v[168:169] op_sel_hi:[1,0]
	v_exp_f32_e32 v124, v124
	v_exp_f32_e32 v125, v125
	v_exp_f32_e32 v126, v126
	v_exp_f32_e32 v127, v127
	v_exp_f32_e32 v116, v116
	v_exp_f32_e32 v117, v117
	v_exp_f32_e32 v118, v118
	v_exp_f32_e32 v119, v119
	v_mad_i64_i32 v[170:171], s[0:1], v149, s52, v[164:165]
	v_pk_fma_f32 v[124:125], v[124:125], v[166:167], v[166:167] op_sel_hi:[1,0,0]
	v_pk_fma_f32 v[126:127], v[126:127], v[166:167], v[166:167] op_sel_hi:[1,0,0]
	v_pk_fma_f32 v[116:117], v[116:117], v[166:167], v[166:167] op_sel_hi:[1,0,0]
	v_pk_fma_f32 v[118:119], v[118:119], v[166:167], v[166:167] op_sel_hi:[1,0,0]
	v_rcp_f32_e32 v124, v124
	v_rcp_f32_e32 v125, v125
	v_rcp_f32_e32 v126, v126
	v_rcp_f32_e32 v127, v127
	v_rcp_f32_e32 v116, v116
	v_rcp_f32_e32 v117, v117
	v_rcp_f32_e32 v118, v118
	v_rcp_f32_e32 v119, v119
	s_nop 0
	v_pk_mul_f32 v[120:121], v[120:121], v[124:125]
	v_pk_mul_f32 v[122:123], v[122:123], v[126:127]
	v_pk_mul_f32 v[112:113], v[112:113], v[116:117]
	v_pk_mul_f32 v[114:115], v[114:115], v[118:119]
	v_cvt_pk_bf16_f32 v124, v120, v121
	v_cvt_pk_bf16_f32 v125, v122, v123
	v_cvt_pk_bf16_f32 v126, v112, v113
	v_cvt_pk_bf16_f32 v127, v114, v115
	global_store_dwordx4 v[170:171], v[124:127], off
	v_fmamk_f32 v166, v156, 0x39800000, v154
	v_rsq_f32_e32 v167, v166
	v_pk_mul_f32 v[104:105], v[108:109], v[104:105]
	v_pk_mul_f32 v[106:107], v[110:111], v[106:107]
	v_pk_mul_f32 v[96:97], v[100:101], v[96:97]
	v_pk_mul_f32 v[98:99], v[102:103], v[98:99]
	v_mul_f32_e32 v168, 0xbfb8aa3b, v167
	v_add_u32_e32 v149, 0x10, v148
	v_pk_mul_f32 v[108:109], v[108:109], v[168:169] op_sel_hi:[1,0]
	v_pk_mul_f32 v[110:111], v[110:111], v[168:169] op_sel_hi:[1,0]
	v_pk_mul_f32 v[100:101], v[100:101], v[168:169] op_sel_hi:[1,0]
	v_pk_mul_f32 v[102:103], v[102:103], v[168:169] op_sel_hi:[1,0]
	v_exp_f32_e32 v108, v108
	v_exp_f32_e32 v109, v109
	v_exp_f32_e32 v110, v110
	v_exp_f32_e32 v111, v111
	v_exp_f32_e32 v100, v100
	v_exp_f32_e32 v101, v101
	v_exp_f32_e32 v102, v102
	v_exp_f32_e32 v103, v103
	v_mad_i64_i32 v[170:171], s[0:1], v149, s52, v[164:165]
	v_pk_fma_f32 v[108:109], v[108:109], v[166:167], v[166:167] op_sel_hi:[1,0,0]
	v_pk_fma_f32 v[110:111], v[110:111], v[166:167], v[166:167] op_sel_hi:[1,0,0]
	v_pk_fma_f32 v[100:101], v[100:101], v[166:167], v[166:167] op_sel_hi:[1,0,0]
	v_pk_fma_f32 v[102:103], v[102:103], v[166:167], v[166:167] op_sel_hi:[1,0,0]
	v_rcp_f32_e32 v108, v108
	v_rcp_f32_e32 v109, v109
	v_rcp_f32_e32 v110, v110
	v_rcp_f32_e32 v111, v111
	v_rcp_f32_e32 v100, v100
	v_rcp_f32_e32 v101, v101
	v_rcp_f32_e32 v102, v102
	v_rcp_f32_e32 v103, v103
	s_nop 0
	v_pk_mul_f32 v[104:105], v[104:105], v[108:109]
	v_pk_mul_f32 v[106:107], v[106:107], v[110:111]
	v_pk_mul_f32 v[96:97], v[96:97], v[100:101]
	v_pk_mul_f32 v[98:99], v[98:99], v[102:103]
	v_cvt_pk_bf16_f32 v108, v104, v105
	v_cvt_pk_bf16_f32 v109, v106, v107
	v_cvt_pk_bf16_f32 v110, v96, v97
	v_cvt_pk_bf16_f32 v111, v98, v99
	global_store_dwordx4 v[170:171], v[108:111], off
	v_fmamk_f32 v166, v157, 0x39800000, v154
	v_rsq_f32_e32 v167, v166
	v_pk_mul_f32 v[88:89], v[92:93], v[88:89]
	v_pk_mul_f32 v[90:91], v[94:95], v[90:91]
	v_pk_mul_f32 v[80:81], v[84:85], v[80:81]
	v_pk_mul_f32 v[82:83], v[86:87], v[82:83]
	v_mul_f32_e32 v168, 0xbfb8aa3b, v167
	v_add_u32_e32 v149, 0x20, v148
	v_pk_mul_f32 v[92:93], v[92:93], v[168:169] op_sel_hi:[1,0]
	v_pk_mul_f32 v[94:95], v[94:95], v[168:169] op_sel_hi:[1,0]
	v_pk_mul_f32 v[84:85], v[84:85], v[168:169] op_sel_hi:[1,0]
	v_pk_mul_f32 v[86:87], v[86:87], v[168:169] op_sel_hi:[1,0]
	v_exp_f32_e32 v92, v92
	v_exp_f32_e32 v93, v93
	v_exp_f32_e32 v94, v94
	v_exp_f32_e32 v95, v95
	v_exp_f32_e32 v84, v84
	v_exp_f32_e32 v85, v85
	v_exp_f32_e32 v86, v86
	v_exp_f32_e32 v87, v87
	v_mad_i64_i32 v[170:171], s[0:1], v149, s52, v[164:165]
	v_pk_fma_f32 v[92:93], v[92:93], v[166:167], v[166:167] op_sel_hi:[1,0,0]
	v_pk_fma_f32 v[94:95], v[94:95], v[166:167], v[166:167] op_sel_hi:[1,0,0]
	v_pk_fma_f32 v[84:85], v[84:85], v[166:167], v[166:167] op_sel_hi:[1,0,0]
	v_pk_fma_f32 v[86:87], v[86:87], v[166:167], v[166:167] op_sel_hi:[1,0,0]
	v_rcp_f32_e32 v92, v92
	v_rcp_f32_e32 v93, v93
	v_rcp_f32_e32 v94, v94
; DI float sigmoidf_(float z) { return 1.0f / (1.0f + __expf(-z)); }
; DI v4u pack8(const f4& a, const f4& b) { v4u w; w.x = cvt_pk_bf16(a[0], a[1]); w.y = cvt_pk_bf16(a[2], a[3]); w.z = cvt_pk_bf16(b[0], b[1]); w.w = cvt_pk_bf16(b[2], b[3]); return w; }
;     DI void operator()(f4 (&acc)[2][2][4][2], const Unit& u, int wr, int wc, int fr, int fq) const {
;     ...
;             for (int m = 0; m < 4; ++m) { const int row = row0 + ai * HALF + m * 16; const float r = __builtin_amdgcn_rsqf(rr[ai][m] * (1.0f / D) + RMS_EPS);
;                 f4 o0, o1;
; #pragma unroll
;                 for (int e = 0; e < 4; ++e) { const float a0 = acc[ai][0][m][0][e] * r, a1 = acc[ai][0][m][1][e] * r;
;                     o0[e] = a0 * sigmoidf_(a0) * (acc[ai][1][m][0][e] * r); o1[e] = a1 * sigmoidf_(a1) * (acc[ai][1][m][1][e] * r); }
;                 *(v4u*)(uout + (size_t)row * DFF + col0) = pack8(o0, o1); }
	v_rcp_f32_e32 v95, v95
	v_rcp_f32_e32 v84, v84
	v_rcp_f32_e32 v85, v85
	v_rcp_f32_e32 v86, v86
	v_rcp_f32_e32 v87, v87
	s_nop 0
	v_pk_mul_f32 v[88:89], v[88:89], v[92:93]
	v_pk_mul_f32 v[90:91], v[90:91], v[94:95]
	v_pk_mul_f32 v[80:81], v[80:81], v[84:85]
	v_pk_mul_f32 v[82:83], v[82:83], v[86:87]
	v_cvt_pk_bf16_f32 v92, v88, v89
	v_cvt_pk_bf16_f32 v93, v90, v91
	v_cvt_pk_bf16_f32 v94, v80, v81
	v_cvt_pk_bf16_f32 v95, v82, v83
	global_store_dwordx4 v[170:171], v[92:95], off
	v_fmamk_f32 v166, v158, 0x39800000, v154
	v_rsq_f32_e32 v167, v166
	v_pk_mul_f32 v[72:73], v[76:77], v[72:73]
	v_pk_mul_f32 v[74:75], v[78:79], v[74:75]
	v_pk_mul_f32 v[64:65], v[68:69], v[64:65]
	v_pk_mul_f32 v[66:67], v[70:71], v[66:67]
	v_mul_f32_e32 v168, 0xbfb8aa3b, v167
	v_add_u32_e32 v149, 0x30, v148
	v_pk_mul_f32 v[76:77], v[76:77], v[168:169] op_sel_hi:[1,0]
	v_pk_mul_f32 v[78:79], v[78:79], v[168:169] op_sel_hi:[1,0]
	v_pk_mul_f32 v[68:69], v[68:69], v[168:169] op_sel_hi:[1,0]
	v_pk_mul_f32 v[70:71], v[70:71], v[168:169] op_sel_hi:[1,0]
	v_exp_f32_e32 v76, v76
	v_exp_f32_e32 v77, v77
	v_exp_f32_e32 v78, v78
	v_exp_f32_e32 v79, v79
	v_exp_f32_e32 v68, v68
	v_exp_f32_e32 v69, v69
	v_exp_f32_e32 v70, v70
	v_exp_f32_e32 v71, v71
	v_mad_i64_i32 v[170:171], s[0:1], v149, s52, v[164:165]
	v_pk_fma_f32 v[76:77], v[76:77], v[166:167], v[166:167] op_sel_hi:[1,0,0]
	v_pk_fma_f32 v[78:79], v[78:79], v[166:167], v[166:167] op_sel_hi:[1,0,0]
	v_pk_fma_f32 v[68:69], v[68:69], v[166:167], v[166:167] op_sel_hi:[1,0,0]
	v_pk_fma_f32 v[70:71], v[70:71], v[166:167], v[166:167] op_sel_hi:[1,0,0]
	v_rcp_f32_e32 v76, v76
	v_rcp_f32_e32 v77, v77
	v_rcp_f32_e32 v78, v78
	v_rcp_f32_e32 v79, v79
	v_rcp_f32_e32 v68, v68
	v_rcp_f32_e32 v69, v69
	v_rcp_f32_e32 v70, v70
	v_rcp_f32_e32 v71, v71
	s_nop 0
	v_pk_mul_f32 v[72:73], v[72:73], v[76:77]
	v_pk_mul_f32 v[74:75], v[74:75], v[78:79]
	v_pk_mul_f32 v[64:65], v[64:65], v[68:69]
	v_pk_mul_f32 v[66:67], v[66:67], v[70:71]
	v_cvt_pk_bf16_f32 v76, v72, v73
	v_cvt_pk_bf16_f32 v77, v74, v75
	v_cvt_pk_bf16_f32 v78, v64, v65
	v_cvt_pk_bf16_f32 v79, v66, v67
	global_store_dwordx4 v[170:171], v[76:79], off
	v_fmamk_f32 v166, v159, 0x39800000, v154
	v_rsq_f32_e32 v167, v166
	v_pk_mul_f32 v[56:57], v[60:61], v[56:57]
	v_pk_mul_f32 v[58:59], v[62:63], v[58:59]
	v_pk_mul_f32 v[48:49], v[52:53], v[48:49]
	v_pk_mul_f32 v[50:51], v[54:55], v[50:51]
	v_mul_f32_e32 v168, 0xbfb8aa3b, v167
	v_add_u32_e32 v149, 0x80, v148
	v_pk_mul_f32 v[60:61], v[60:61], v[168:169] op_sel_hi:[1,0]
	v_pk_mul_f32 v[62:63], v[62:63], v[168:169] op_sel_hi:[1,0]
	v_pk_mul_f32 v[52:53], v[52:53], v[168:169] op_sel_hi:[1,0]
	v_pk_mul_f32 v[54:55], v[54:55], v[168:169] op_sel_hi:[1,0]
	v_exp_f32_e32 v60, v60
	v_exp_f32_e32 v61, v61
	v_exp_f32_e32 v62, v62
	v_exp_f32_e32 v63, v63
	v_exp_f32_e32 v52, v52
	v_exp_f32_e32 v53, v53
	v_exp_f32_e32 v54, v54
	v_exp_f32_e32 v55, v55
	v_mad_i64_i32 v[170:171], s[0:1], v149, s52, v[164:165]
	v_pk_fma_f32 v[60:61], v[60:61], v[166:167], v[166:167] op_sel_hi:[1,0,0]
	v_pk_fma_f32 v[62:63], v[62:63], v[166:167], v[166:167] op_sel_hi:[1,0,0]
	v_pk_fma_f32 v[52:53], v[52:53], v[166:167], v[166:167] op_sel_hi:[1,0,0]
	v_pk_fma_f32 v[54:55], v[54:55], v[166:167], v[166:167] op_sel_hi:[1,0,0]
	v_rcp_f32_e32 v60, v60
	v_rcp_f32_e32 v61, v61
	v_rcp_f32_e32 v62, v62
	v_rcp_f32_e32 v63, v63
	v_rcp_f32_e32 v52, v52
	v_rcp_f32_e32 v53, v53
	v_rcp_f32_e32 v54, v54
	v_rcp_f32_e32 v55, v55
	s_nop 0
	v_pk_mul_f32 v[56:57], v[56:57], v[60:61]
	v_pk_mul_f32 v[58:59], v[58:59], v[62:63]
	v_pk_mul_f32 v[48:49], v[48:49], v[52:53]
	v_pk_mul_f32 v[50:51], v[50:51], v[54:55]
	v_cvt_pk_bf16_f32 v60, v56, v57
	v_cvt_pk_bf16_f32 v61, v58, v59
	v_cvt_pk_bf16_f32 v62, v48, v49
	v_cvt_pk_bf16_f32 v63, v50, v51
	global_store_dwordx4 v[170:171], v[60:63], off
	v_fmamk_f32 v166, v160, 0x39800000, v154
	v_rsq_f32_e32 v167, v166
	v_pk_mul_f32 v[40:41], v[44:45], v[40:41]
	v_pk_mul_f32 v[42:43], v[46:47], v[42:43]
	v_pk_mul_f32 v[32:33], v[36:37], v[32:33]
	v_pk_mul_f32 v[34:35], v[38:39], v[34:35]
	v_mul_f32_e32 v168, 0xbfb8aa3b, v167
	v_add_u32_e32 v149, 0x90, v148
	v_pk_mul_f32 v[44:45], v[44:45], v[168:169] op_sel_hi:[1,0]
	v_pk_mul_f32 v[46:47], v[46:47], v[168:169] op_sel_hi:[1,0]
	v_pk_mul_f32 v[36:37], v[36:37], v[168:169] op_sel_hi:[1,0]
	v_pk_mul_f32 v[38:39], v[38:39], v[168:169] op_sel_hi:[1,0]
	v_exp_f32_e32 v44, v44
	v_exp_f32_e32 v45, v45
	v_exp_f32_e32 v46, v46
	v_exp_f32_e32 v47, v47
; #define PG8_BAR __builtin_amdgcn_s_barrier()
; DI float sigmoidf_(float z) { return 1.0f / (1.0f + __expf(-z)); }
; DI v4u pack8(const f4& a, const f4& b) { v4u w; w.x = cvt_pk_bf16(a[0], a[1]); w.y = cvt_pk_bf16(a[2], a[3]); w.z = cvt_pk_bf16(b[0], b[1]); w.w = cvt_pk_bf16(b[2], b[3]); return w; }
; template <class Epi, class Sched, bool ALIGN_EPI = false, bool SP2 = false>
; __device__ __forceinline__ void gemm_phase(PG8_LAS unsigned char* lds, const Gemm g, const Sched& S, const Epi& E, const int wid) {
;     ...
;         if constexpr (ALIGN_EPI) { if (wr == 0) PG8_BAR; }
;         if constexpr (!Epi::AFTER_DRAIN) { E(acc, cur, wr, wc, fr, fq); S.done(cur); }
;         if (!has_next) break;
;         if (!Epi::CHAIN || !E.keep(cur)) {
; #pragma unroll
;         for (int a = 0; a < 2; ++a)
; #pragma unroll
;             for (int b = 0; b < 2; ++b)
; #pragma unroll
;                 for (int m = 0; m < 4; ++m)
; #pragma unroll
;                     for (int n = 0; n < 2; ++n) acc[a][b][m][n] = (f32x4){0.f, 0.f, 0.f, 0.f};
;         }
;         cur = nxt; cA = nA; cB = nB; ++ui;
;         if constexpr (ALIGN_EPI) { if (wr == 1) PG8_BAR; }
;     DI void operator()(f4 (&acc)[2][2][4][2], const Unit& u, int wr, int wc, int fr, int fq) const {
;     ...
;             for (int m = 0; m < 4; ++m) { const int row = row0 + ai * HALF + m * 16; const float r = __builtin_amdgcn_rsqf(rr[ai][m] * (1.0f / D) + RMS_EPS);
;                 f4 o0, o1;
; #pragma unroll
;                 for (int e = 0; e < 4; ++e) { const float a0 = acc[ai][0][m][0][e] * r, a1 = acc[ai][0][m][1][e] * r;
;                     o0[e] = a0 * sigmoidf_(a0) * (acc[ai][1][m][0][e] * r); o1[e] = a1 * sigmoidf_(a1) * (acc[ai][1][m][1][e] * r); }
;                 *(v4u*)(uout + (size_t)row * DFF + col0) = pack8(o0, o1); }
	v_exp_f32_e32 v36, v36
	v_exp_f32_e32 v37, v37
	v_exp_f32_e32 v38, v38
	v_exp_f32_e32 v39, v39
	v_mad_i64_i32 v[170:171], s[0:1], v149, s52, v[164:165]
	v_pk_fma_f32 v[44:45], v[44:45], v[166:167], v[166:167] op_sel_hi:[1,0,0]
	v_pk_fma_f32 v[46:47], v[46:47], v[166:167], v[166:167] op_sel_hi:[1,0,0]
	v_pk_fma_f32 v[36:37], v[36:37], v[166:167], v[166:167] op_sel_hi:[1,0,0]
	v_pk_fma_f32 v[38:39], v[38:39], v[166:167], v[166:167] op_sel_hi:[1,0,0]
	v_rcp_f32_e32 v44, v44
	v_rcp_f32_e32 v45, v45
	v_rcp_f32_e32 v46, v46
	v_rcp_f32_e32 v47, v47
	v_rcp_f32_e32 v36, v36
	v_rcp_f32_e32 v37, v37
	v_rcp_f32_e32 v38, v38
	v_rcp_f32_e32 v39, v39
	s_nop 0
	v_pk_mul_f32 v[40:41], v[40:41], v[44:45]
	v_pk_mul_f32 v[42:43], v[42:43], v[46:47]
	v_pk_mul_f32 v[32:33], v[32:33], v[36:37]
	v_pk_mul_f32 v[34:35], v[34:35], v[38:39]
	v_cvt_pk_bf16_f32 v44, v40, v41
	v_cvt_pk_bf16_f32 v45, v42, v43
	v_cvt_pk_bf16_f32 v46, v32, v33
	v_cvt_pk_bf16_f32 v47, v34, v35
	global_store_dwordx4 v[170:171], v[44:47], off
	v_fmamk_f32 v166, v161, 0x39800000, v154
	v_rsq_f32_e32 v167, v166
	v_pk_mul_f32 v[24:25], v[28:29], v[24:25]
	v_pk_mul_f32 v[26:27], v[30:31], v[26:27]
	v_pk_mul_f32 v[16:17], v[20:21], v[16:17]
	v_pk_mul_f32 v[18:19], v[22:23], v[18:19]
	v_mul_f32_e32 v168, 0xbfb8aa3b, v167
	v_add_u32_e32 v149, 0xa0, v148
	v_pk_mul_f32 v[28:29], v[28:29], v[168:169] op_sel_hi:[1,0]
	v_pk_mul_f32 v[30:31], v[30:31], v[168:169] op_sel_hi:[1,0]
	v_pk_mul_f32 v[20:21], v[20:21], v[168:169] op_sel_hi:[1,0]
	v_pk_mul_f32 v[22:23], v[22:23], v[168:169] op_sel_hi:[1,0]
	v_exp_f32_e32 v28, v28
	v_exp_f32_e32 v29, v29
	v_exp_f32_e32 v30, v30
	v_exp_f32_e32 v31, v31
	v_exp_f32_e32 v20, v20
	v_exp_f32_e32 v21, v21
	v_exp_f32_e32 v22, v22
	v_exp_f32_e32 v23, v23
	v_mad_i64_i32 v[170:171], s[0:1], v149, s52, v[164:165]
	v_pk_fma_f32 v[28:29], v[28:29], v[166:167], v[166:167] op_sel_hi:[1,0,0]
	v_pk_fma_f32 v[30:31], v[30:31], v[166:167], v[166:167] op_sel_hi:[1,0,0]
	v_pk_fma_f32 v[20:21], v[20:21], v[166:167], v[166:167] op_sel_hi:[1,0,0]
	v_pk_fma_f32 v[22:23], v[22:23], v[166:167], v[166:167] op_sel_hi:[1,0,0]
	v_rcp_f32_e32 v28, v28
	v_rcp_f32_e32 v29, v29
	v_rcp_f32_e32 v30, v30
	v_rcp_f32_e32 v31, v31
	v_rcp_f32_e32 v20, v20
	v_rcp_f32_e32 v21, v21
	v_rcp_f32_e32 v22, v22
	v_rcp_f32_e32 v23, v23
	s_nop 0
	v_pk_mul_f32 v[24:25], v[24:25], v[28:29]
	v_pk_mul_f32 v[26:27], v[26:27], v[30:31]
	v_pk_mul_f32 v[16:17], v[16:17], v[20:21]
	v_pk_mul_f32 v[18:19], v[18:19], v[22:23]
	v_cvt_pk_bf16_f32 v28, v24, v25
	v_cvt_pk_bf16_f32 v29, v26, v27
	v_cvt_pk_bf16_f32 v30, v16, v17
	v_cvt_pk_bf16_f32 v31, v18, v19
	global_store_dwordx4 v[170:171], v[28:31], off
	v_fmamk_f32 v166, v162, 0x39800000, v154
	v_rsq_f32_e32 v167, v166
	v_pk_mul_f32 v[8:9], v[12:13], v[8:9]
	v_pk_mul_f32 v[10:11], v[14:15], v[10:11]
	v_pk_mul_f32 v[0:1], v[4:5], v[0:1]
	v_pk_mul_f32 v[2:3], v[6:7], v[2:3]
	v_mul_f32_e32 v168, 0xbfb8aa3b, v167
	v_add_u32_e32 v149, 0xb0, v148
	v_pk_mul_f32 v[12:13], v[12:13], v[168:169] op_sel_hi:[1,0]
	v_pk_mul_f32 v[14:15], v[14:15], v[168:169] op_sel_hi:[1,0]
	v_pk_mul_f32 v[4:5], v[4:5], v[168:169] op_sel_hi:[1,0]
	v_pk_mul_f32 v[6:7], v[6:7], v[168:169] op_sel_hi:[1,0]
	v_exp_f32_e32 v12, v12
	v_exp_f32_e32 v13, v13
	v_exp_f32_e32 v14, v14
	v_exp_f32_e32 v15, v15
	v_exp_f32_e32 v4, v4
	v_exp_f32_e32 v5, v5
	v_exp_f32_e32 v6, v6
	v_exp_f32_e32 v7, v7
	v_mad_i64_i32 v[170:171], s[0:1], v149, s52, v[164:165]
	v_pk_fma_f32 v[12:13], v[12:13], v[166:167], v[166:167] op_sel_hi:[1,0,0]
	v_pk_fma_f32 v[14:15], v[14:15], v[166:167], v[166:167] op_sel_hi:[1,0,0]
	v_pk_fma_f32 v[4:5], v[4:5], v[166:167], v[166:167] op_sel_hi:[1,0,0]
	v_pk_fma_f32 v[6:7], v[6:7], v[166:167], v[166:167] op_sel_hi:[1,0,0]
	v_rcp_f32_e32 v12, v12
	v_rcp_f32_e32 v13, v13
	v_rcp_f32_e32 v14, v14
	v_rcp_f32_e32 v15, v15
	v_rcp_f32_e32 v4, v4
	v_rcp_f32_e32 v5, v5
	v_rcp_f32_e32 v6, v6
	v_rcp_f32_e32 v7, v7
	s_nop 0
	v_pk_mul_f32 v[8:9], v[8:9], v[12:13]
	v_pk_mul_f32 v[10:11], v[10:11], v[14:15]
	v_pk_mul_f32 v[0:1], v[0:1], v[4:5]
	v_pk_mul_f32 v[2:3], v[2:3], v[6:7]
	s_andn2_b64 vcc, exec, s[4:5]
	s_mov_b64 s[0:1], -1
	v_cvt_pk_bf16_f32 v12, v8, v9
	v_cvt_pk_bf16_f32 v13, v10, v11
	v_cvt_pk_bf16_f32 v14, v0, v1
	v_cvt_pk_bf16_f32 v15, v2, v3
	global_store_dwordx4 v[170:171], v[12:15], off
	s_cbranch_vccnz .LBB0_2802
	s_andn2_b64 vcc, exec, s[12:13]
	s_cbranch_vccnz .LBB0_2801
	s_barrier
	s_branch .LBB0_2801

; __device__ __forceinline__ int lane_opaque() { int l; asm volatile("v_mbcnt_lo_u32_b32 %0, -1, 0\n\tv_mbcnt_hi_u32_b32 %0, -1, %0" : "=v"(l)); return l; }
; DI float sigmoidf_(float z) { return 1.0f / (1.0f + __expf(-z)); }
; DI v4u pack8(const f4& a, const f4& b) { v4u w; w.x = cvt_pk_bf16(a[0], a[1]); w.y = cvt_pk_bf16(a[2], a[3]); w.z = cvt_pk_bf16(b[0], b[1]); w.w = cvt_pk_bf16(b[2], b[3]); return w; }
;     DI void operator()(f4 (&acc)[2][2][4][2], const Unit& u, int wr, int wc, int fr, int fq) const {
;         { const int ln_ = lane_opaque(); fr = ln_ & 15; fq = ln_ >> 4; }
;         const int row0 = u.pm * BM + wr * 64 + fr, col0 = u.pn * HALF + wc * 32 + 8 * fq;
;         float rr[2][4];
; #pragma unroll
;         for (int ai = 0; ai < 2; ++ai)
; #pragma unroll
;             for (int m = 0; m < 4; ++m) rr[ai][m] = ss[row0 + ai * HALF + m * 16];
; #pragma unroll
;         for (int ai = 0; ai < 2; ++ai)
; #pragma unroll
;             for (int m = 0; m < 4; ++m) { const int row = row0 + ai * HALF + m * 16; const float r = __builtin_amdgcn_rsqf(rr[ai][m] * (1.0f / D) + RMS_EPS);
;                 f4 o0, o1;
; #pragma unroll
;                 for (int e = 0; e < 4; ++e) { const float a0 = acc[ai][0][m][0][e] * r, a1 = acc[ai][0][m][1][e] * r;
;                     o0[e] = a0 * sigmoidf_(a0) * (acc[ai][1][m][0][e] * r); o1[e] = a1 * sigmoidf_(a1) * (acc[ai][1][m][1][e] * r); }
;                 *(v4u*)(uout + (size_t)row * DFF + col0) = pack8(o0, o1); }
.LBB0_2829:
	s_lshl_b32 s0, s0, 8
	s_add_i32 s0, s0, s36
	v_mbcnt_lo_u32_b32 v144, -1, 0
	v_mbcnt_hi_u32_b32 v144, -1, v144
	v_and_or_b32 v148, v144, 15, s0
	v_ashrrev_i32_e32 v149, 31, v148
	v_lshl_add_u64 v[146:147], v[148:149], 2, s[10:11]
	global_load_dword v155, v[146:147], off
	global_load_dword v156, v[146:147], off offset:64
	global_load_dword v157, v[146:147], off offset:128
	global_load_dword v158, v[146:147], off offset:192
	global_load_dword v159, v[146:147], off offset:512
	global_load_dword v160, v[146:147], off offset:576
	global_load_dword v161, v[146:147], off offset:640
	global_load_dword v162, v[146:147], off offset:704
	s_lshl_b32 s0, s1, 7
	s_or_b32 s0, s0, s37
	v_ashrrev_i32_e32 v145, 1, v144
	v_and_b32_e32 v145, -8, v145
	v_add_u32_e32 v164, s0, v145
	v_ashrrev_i32_e32 v165, 31, v164
	v_lshlrev_b64 v[164:165], 1, v[164:165]
	v_lshl_add_u64 v[164:165], v[164:165], 0, s[14:15]
	s_waitcnt vmcnt(0)
	v_fmamk_f32 v166, v155, 0x39800000, v154
	v_rsq_f32_e32 v167, v166
	v_pk_mul_f32 v[120:121], v[124:125], v[120:121]
	v_pk_mul_f32 v[122:123], v[126:127], v[122:123]
	v_pk_mul_f32 v[112:113], v[116:117], v[112:113]
	v_pk_mul_f32 v[114:115], v[118:119], v[114:115]
	v_mul_f32_e32 v168, 0xbfb8aa3b, v167
	v_mov_b32_e32 v149, v148
	v_pk_mul_f32 v[124:125], v[124:125], v[168:169] op_sel_hi:[1,0]
	v_pk_mul_f32 v[126:127], v[126:127], v[168:169] op_sel_hi:[1,0]
	v_pk_mul_f32 v[116:117], v[116:117], v[168:169] op_sel_hi:[1,0]
	v_pk_mul_f32 v[118:119], v[118:119], v[168:169] op_sel_hi:[1,0]
	v_exp_f32_e32 v124, v124
	v_exp_f32_e32 v125, v125
	v_exp_f32_e32 v126, v126
	v_exp_f32_e32 v127, v127
	v_exp_f32_e32 v116, v116
	v_exp_f32_e32 v117, v117
	v_exp_f32_e32 v118, v118
	v_exp_f32_e32 v119, v119
	v_mad_i64_i32 v[170:171], s[0:1], v149, s53, v[164:165]
	v_pk_fma_f32 v[124:125], v[124:125], v[166:167], v[166:167] op_sel_hi:[1,0,0]
	v_pk_fma_f32 v[126:127], v[126:127], v[166:167], v[166:167] op_sel_hi:[1,0,0]
	v_pk_fma_f32 v[116:117], v[116:117], v[166:167], v[166:167] op_sel_hi:[1,0,0]
	v_pk_fma_f32 v[118:119], v[118:119], v[166:167], v[166:167] op_sel_hi:[1,0,0]
	v_rcp_f32_e32 v124, v124
	v_rcp_f32_e32 v125, v125
	v_rcp_f32_e32 v126, v126
	v_rcp_f32_e32 v127, v127
	v_rcp_f32_e32 v116, v116
	v_rcp_f32_e32 v117, v117
	v_rcp_f32_e32 v118, v118
	v_rcp_f32_e32 v119, v119
	s_nop 0
	v_pk_mul_f32 v[120:121], v[120:121], v[124:125]
	v_pk_mul_f32 v[122:123], v[122:123], v[126:127]
	v_pk_mul_f32 v[112:113], v[112:113], v[116:117]
	v_pk_mul_f32 v[114:115], v[114:115], v[118:119]
	v_cvt_pk_bf16_f32 v124, v120, v121
	v_cvt_pk_bf16_f32 v125, v122, v123
	v_cvt_pk_bf16_f32 v126, v112, v113
	v_cvt_pk_bf16_f32 v127, v114, v115
	global_store_dwordx4 v[170:171], v[124:127], off
	v_fmamk_f32 v166, v156, 0x39800000, v154
	v_rsq_f32_e32 v167, v166
	v_pk_mul_f32 v[104:105], v[108:109], v[104:105]
	v_pk_mul_f32 v[106:107], v[110:111], v[106:107]
	v_pk_mul_f32 v[96:97], v[100:101], v[96:97]
	v_pk_mul_f32 v[98:99], v[102:103], v[98:99]
	v_mul_f32_e32 v168, 0xbfb8aa3b, v167
	v_add_u32_e32 v149, 0x10, v148
	v_pk_mul_f32 v[108:109], v[108:109], v[168:169] op_sel_hi:[1,0]
	v_pk_mul_f32 v[110:111], v[110:111], v[168:169] op_sel_hi:[1,0]
	v_pk_mul_f32 v[100:101], v[100:101], v[168:169] op_sel_hi:[1,0]
	v_pk_mul_f32 v[102:103], v[102:103], v[168:169] op_sel_hi:[1,0]
	v_exp_f32_e32 v108, v108
	v_exp_f32_e32 v109, v109
	v_exp_f32_e32 v110, v110
	v_exp_f32_e32 v111, v111
	v_exp_f32_e32 v100, v100
	v_exp_f32_e32 v101, v101
	v_exp_f32_e32 v102, v102
	v_exp_f32_e32 v103, v103
	v_mad_i64_i32 v[170:171], s[0:1], v149, s53, v[164:165]
	v_pk_fma_f32 v[108:109], v[108:109], v[166:167], v[166:167] op_sel_hi:[1,0,0]
	v_pk_fma_f32 v[110:111], v[110:111], v[166:167], v[166:167] op_sel_hi:[1,0,0]
	v_pk_fma_f32 v[100:101], v[100:101], v[166:167], v[166:167] op_sel_hi:[1,0,0]
	v_pk_fma_f32 v[102:103], v[102:103], v[166:167], v[166:167] op_sel_hi:[1,0,0]
	v_rcp_f32_e32 v108, v108
	v_rcp_f32_e32 v109, v109
	v_rcp_f32_e32 v110, v110
	v_rcp_f32_e32 v111, v111
	v_rcp_f32_e32 v100, v100
	v_rcp_f32_e32 v101, v101
	v_rcp_f32_e32 v102, v102
	v_rcp_f32_e32 v103, v103
	s_nop 0
	v_pk_mul_f32 v[104:105], v[104:105], v[108:109]
	v_pk_mul_f32 v[106:107], v[106:107], v[110:111]
	v_pk_mul_f32 v[96:97], v[96:97], v[100:101]
	v_pk_mul_f32 v[98:99], v[98:99], v[102:103]
	v_cvt_pk_bf16_f32 v108, v104, v105
	v_cvt_pk_bf16_f32 v109, v106, v107
	v_cvt_pk_bf16_f32 v110, v96, v97
	v_cvt_pk_bf16_f32 v111, v98, v99
	global_store_dwordx4 v[170:171], v[108:111], off
	v_fmamk_f32 v166, v157, 0x39800000, v154
	v_rsq_f32_e32 v167, v166
	v_pk_mul_f32 v[88:89], v[92:93], v[88:89]
	v_pk_mul_f32 v[90:91], v[94:95], v[90:91]
	v_pk_mul_f32 v[80:81], v[84:85], v[80:81]
	v_pk_mul_f32 v[82:83], v[86:87], v[82:83]
	v_mul_f32_e32 v168, 0xbfb8aa3b, v167
	v_add_u32_e32 v149, 0x20, v148
	v_pk_mul_f32 v[92:93], v[92:93], v[168:169] op_sel_hi:[1,0]
	v_pk_mul_f32 v[94:95], v[94:95], v[168:169] op_sel_hi:[1,0]
	v_pk_mul_f32 v[84:85], v[84:85], v[168:169] op_sel_hi:[1,0]
	v_pk_mul_f32 v[86:87], v[86:87], v[168:169] op_sel_hi:[1,0]
	v_exp_f32_e32 v92, v92
	v_exp_f32_e32 v93, v93
	v_exp_f32_e32 v94, v94
	v_exp_f32_e32 v95, v95
	v_exp_f32_e32 v84, v84
	v_exp_f32_e32 v85, v85
	v_exp_f32_e32 v86, v86
	v_exp_f32_e32 v87, v87
	v_mad_i64_i32 v[170:171], s[0:1], v149, s53, v[164:165]
	v_pk_fma_f32 v[92:93], v[92:93], v[166:167], v[166:167] op_sel_hi:[1,0,0]
	v_pk_fma_f32 v[94:95], v[94:95], v[166:167], v[166:167] op_sel_hi:[1,0,0]
	v_pk_fma_f32 v[84:85], v[84:85], v[166:167], v[166:167] op_sel_hi:[1,0,0]
	v_pk_fma_f32 v[86:87], v[86:87], v[166:167], v[166:167] op_sel_hi:[1,0,0]
	v_rcp_f32_e32 v92, v92
	v_rcp_f32_e32 v93, v93
	v_rcp_f32_e32 v94, v94
; DI float sigmoidf_(float z) { return 1.0f / (1.0f + __expf(-z)); }
; DI v4u pack8(const f4& a, const f4& b) { v4u w; w.x = cvt_pk_bf16(a[0], a[1]); w.y = cvt_pk_bf16(a[2], a[3]); w.z = cvt_pk_bf16(b[0], b[1]); w.w = cvt_pk_bf16(b[2], b[3]); return w; }
;     DI void operator()(f4 (&acc)[2][2][4][2], const Unit& u, int wr, int wc, int fr, int fq) const {
;     ...
;             for (int m = 0; m < 4; ++m) { const int row = row0 + ai * HALF + m * 16; const float r = __builtin_amdgcn_rsqf(rr[ai][m] * (1.0f / D) + RMS_EPS);
;                 f4 o0, o1;
; #pragma unroll
;                 for (int e = 0; e < 4; ++e) { const float a0 = acc[ai][0][m][0][e] * r, a1 = acc[ai][0][m][1][e] * r;
;                     o0[e] = a0 * sigmoidf_(a0) * (acc[ai][1][m][0][e] * r); o1[e] = a1 * sigmoidf_(a1) * (acc[ai][1][m][1][e] * r); }
;                 *(v4u*)(uout + (size_t)row * DFF + col0) = pack8(o0, o1); }
	v_rcp_f32_e32 v95, v95
	v_rcp_f32_e32 v84, v84
	v_rcp_f32_e32 v85, v85
	v_rcp_f32_e32 v86, v86
	v_rcp_f32_e32 v87, v87
	s_nop 0
	v_pk_mul_f32 v[88:89], v[88:89], v[92:93]
	v_pk_mul_f32 v[90:91], v[90:91], v[94:95]
	v_pk_mul_f32 v[80:81], v[80:81], v[84:85]
	v_pk_mul_f32 v[82:83], v[82:83], v[86:87]
	v_cvt_pk_bf16_f32 v92, v88, v89
	v_cvt_pk_bf16_f32 v93, v90, v91
	v_cvt_pk_bf16_f32 v94, v80, v81
	v_cvt_pk_bf16_f32 v95, v82, v83
	global_store_dwordx4 v[170:171], v[92:95], off
	v_fmamk_f32 v166, v158, 0x39800000, v154
	v_rsq_f32_e32 v167, v166
	v_pk_mul_f32 v[72:73], v[76:77], v[72:73]
	v_pk_mul_f32 v[74:75], v[78:79], v[74:75]
	v_pk_mul_f32 v[64:65], v[68:69], v[64:65]
	v_pk_mul_f32 v[66:67], v[70:71], v[66:67]
	v_mul_f32_e32 v168, 0xbfb8aa3b, v167
	v_add_u32_e32 v149, 0x30, v148
	v_pk_mul_f32 v[76:77], v[76:77], v[168:169] op_sel_hi:[1,0]
	v_pk_mul_f32 v[78:79], v[78:79], v[168:169] op_sel_hi:[1,0]
	v_pk_mul_f32 v[68:69], v[68:69], v[168:169] op_sel_hi:[1,0]
	v_pk_mul_f32 v[70:71], v[70:71], v[168:169] op_sel_hi:[1,0]
	v_exp_f32_e32 v76, v76
	v_exp_f32_e32 v77, v77
	v_exp_f32_e32 v78, v78
	v_exp_f32_e32 v79, v79
	v_exp_f32_e32 v68, v68
	v_exp_f32_e32 v69, v69
	v_exp_f32_e32 v70, v70
	v_exp_f32_e32 v71, v71
	v_mad_i64_i32 v[170:171], s[0:1], v149, s53, v[164:165]
	v_pk_fma_f32 v[76:77], v[76:77], v[166:167], v[166:167] op_sel_hi:[1,0,0]
	v_pk_fma_f32 v[78:79], v[78:79], v[166:167], v[166:167] op_sel_hi:[1,0,0]
	v_pk_fma_f32 v[68:69], v[68:69], v[166:167], v[166:167] op_sel_hi:[1,0,0]
	v_pk_fma_f32 v[70:71], v[70:71], v[166:167], v[166:167] op_sel_hi:[1,0,0]
	v_rcp_f32_e32 v76, v76
	v_rcp_f32_e32 v77, v77
	v_rcp_f32_e32 v78, v78
	v_rcp_f32_e32 v79, v79
	v_rcp_f32_e32 v68, v68
	v_rcp_f32_e32 v69, v69
	v_rcp_f32_e32 v70, v70
	v_rcp_f32_e32 v71, v71
	s_nop 0
	v_pk_mul_f32 v[72:73], v[72:73], v[76:77]
	v_pk_mul_f32 v[74:75], v[74:75], v[78:79]
	v_pk_mul_f32 v[64:65], v[64:65], v[68:69]
	v_pk_mul_f32 v[66:67], v[66:67], v[70:71]
	v_cvt_pk_bf16_f32 v76, v72, v73
	v_cvt_pk_bf16_f32 v77, v74, v75
	v_cvt_pk_bf16_f32 v78, v64, v65
	v_cvt_pk_bf16_f32 v79, v66, v67
	global_store_dwordx4 v[170:171], v[76:79], off
	v_fmamk_f32 v166, v159, 0x39800000, v154
	v_rsq_f32_e32 v167, v166
	v_pk_mul_f32 v[56:57], v[60:61], v[56:57]
	v_pk_mul_f32 v[58:59], v[62:63], v[58:59]
	v_pk_mul_f32 v[48:49], v[52:53], v[48:49]
	v_pk_mul_f32 v[50:51], v[54:55], v[50:51]
	v_mul_f32_e32 v168, 0xbfb8aa3b, v167
	v_add_u32_e32 v149, 0x80, v148
	v_pk_mul_f32 v[60:61], v[60:61], v[168:169] op_sel_hi:[1,0]
	v_pk_mul_f32 v[62:63], v[62:63], v[168:169] op_sel_hi:[1,0]
	v_pk_mul_f32 v[52:53], v[52:53], v[168:169] op_sel_hi:[1,0]
	v_pk_mul_f32 v[54:55], v[54:55], v[168:169] op_sel_hi:[1,0]
	v_exp_f32_e32 v60, v60
	v_exp_f32_e32 v61, v61
	v_exp_f32_e32 v62, v62
	v_exp_f32_e32 v63, v63
	v_exp_f32_e32 v52, v52
	v_exp_f32_e32 v53, v53
	v_exp_f32_e32 v54, v54
	v_exp_f32_e32 v55, v55
	v_mad_i64_i32 v[170:171], s[0:1], v149, s53, v[164:165]
	v_pk_fma_f32 v[60:61], v[60:61], v[166:167], v[166:167] op_sel_hi:[1,0,0]
	v_pk_fma_f32 v[62:63], v[62:63], v[166:167], v[166:167] op_sel_hi:[1,0,0]
	v_pk_fma_f32 v[52:53], v[52:53], v[166:167], v[166:167] op_sel_hi:[1,0,0]
	v_pk_fma_f32 v[54:55], v[54:55], v[166:167], v[166:167] op_sel_hi:[1,0,0]
	v_rcp_f32_e32 v60, v60
	v_rcp_f32_e32 v61, v61
	v_rcp_f32_e32 v62, v62
	v_rcp_f32_e32 v63, v63
	v_rcp_f32_e32 v52, v52
	v_rcp_f32_e32 v53, v53
	v_rcp_f32_e32 v54, v54
	v_rcp_f32_e32 v55, v55
	s_nop 0
	v_pk_mul_f32 v[56:57], v[56:57], v[60:61]
	v_pk_mul_f32 v[58:59], v[58:59], v[62:63]
	v_pk_mul_f32 v[48:49], v[48:49], v[52:53]
	v_pk_mul_f32 v[50:51], v[50:51], v[54:55]
	v_cvt_pk_bf16_f32 v60, v56, v57
	v_cvt_pk_bf16_f32 v61, v58, v59
	v_cvt_pk_bf16_f32 v62, v48, v49
	v_cvt_pk_bf16_f32 v63, v50, v51
	global_store_dwordx4 v[170:171], v[60:63], off
	v_fmamk_f32 v166, v160, 0x39800000, v154
	v_rsq_f32_e32 v167, v166
	v_pk_mul_f32 v[40:41], v[44:45], v[40:41]
	v_pk_mul_f32 v[42:43], v[46:47], v[42:43]
	v_pk_mul_f32 v[32:33], v[36:37], v[32:33]
	v_pk_mul_f32 v[34:35], v[38:39], v[34:35]
	v_mul_f32_e32 v168, 0xbfb8aa3b, v167
	v_add_u32_e32 v149, 0x90, v148
	v_pk_mul_f32 v[44:45], v[44:45], v[168:169] op_sel_hi:[1,0]
	v_pk_mul_f32 v[46:47], v[46:47], v[168:169] op_sel_hi:[1,0]
	v_pk_mul_f32 v[36:37], v[36:37], v[168:169] op_sel_hi:[1,0]
	v_pk_mul_f32 v[38:39], v[38:39], v[168:169] op_sel_hi:[1,0]
	v_exp_f32_e32 v44, v44
	v_exp_f32_e32 v45, v45
	v_exp_f32_e32 v46, v46
	v_exp_f32_e32 v47, v47
; #define PG8_BAR __builtin_amdgcn_s_barrier()
; DI float sigmoidf_(float z) { return 1.0f / (1.0f + __expf(-z)); }
; DI v4u pack8(const f4& a, const f4& b) { v4u w; w.x = cvt_pk_bf16(a[0], a[1]); w.y = cvt_pk_bf16(a[2], a[3]); w.z = cvt_pk_bf16(b[0], b[1]); w.w = cvt_pk_bf16(b[2], b[3]); return w; }
; template <class Epi, class Sched, bool ALIGN_EPI = false, bool SP2 = false>
; __device__ __forceinline__ void gemm_phase(PG8_LAS unsigned char* lds, const Gemm g, const Sched& S, const Epi& E, const int wid) {
;     ...
;         if constexpr (ALIGN_EPI) { if (wr == 0) PG8_BAR; }
;         if constexpr (!Epi::AFTER_DRAIN) { E(acc, cur, wr, wc, fr, fq); S.done(cur); }
;         if (!has_next) break;
;         if (!Epi::CHAIN || !E.keep(cur)) {
; #pragma unroll
;         for (int a = 0; a < 2; ++a)
; #pragma unroll
;             for (int b = 0; b < 2; ++b)
; #pragma unroll
;                 for (int m = 0; m < 4; ++m)
; #pragma unroll
;                     for (int n = 0; n < 2; ++n) acc[a][b][m][n] = (f32x4){0.f, 0.f, 0.f, 0.f};
;         }
;         cur = nxt; cA = nA; cB = nB; ++ui;
;         if constexpr (ALIGN_EPI) { if (wr == 1) PG8_BAR; }
;     DI void operator()(f4 (&acc)[2][2][4][2], const Unit& u, int wr, int wc, int fr, int fq) const {
;     ...
;             for (int m = 0; m < 4; ++m) { const int row = row0 + ai * HALF + m * 16; const float r = __builtin_amdgcn_rsqf(rr[ai][m] * (1.0f / D) + RMS_EPS);
;                 f4 o0, o1;
; #pragma unroll
;                 for (int e = 0; e < 4; ++e) { const float a0 = acc[ai][0][m][0][e] * r, a1 = acc[ai][0][m][1][e] * r;
;                     o0[e] = a0 * sigmoidf_(a0) * (acc[ai][1][m][0][e] * r); o1[e] = a1 * sigmoidf_(a1) * (acc[ai][1][m][1][e] * r); }
;                 *(v4u*)(uout + (size_t)row * DFF + col0) = pack8(o0, o1); }
	v_exp_f32_e32 v36, v36
	v_exp_f32_e32 v37, v37
	v_exp_f32_e32 v38, v38
	v_exp_f32_e32 v39, v39
	v_mad_i64_i32 v[170:171], s[0:1], v149, s53, v[164:165]
	v_pk_fma_f32 v[44:45], v[44:45], v[166:167], v[166:167] op_sel_hi:[1,0,0]
	v_pk_fma_f32 v[46:47], v[46:47], v[166:167], v[166:167] op_sel_hi:[1,0,0]
	v_pk_fma_f32 v[36:37], v[36:37], v[166:167], v[166:167] op_sel_hi:[1,0,0]
	v_pk_fma_f32 v[38:39], v[38:39], v[166:167], v[166:167] op_sel_hi:[1,0,0]
	v_rcp_f32_e32 v44, v44
	v_rcp_f32_e32 v45, v45
	v_rcp_f32_e32 v46, v46
	v_rcp_f32_e32 v47, v47
	v_rcp_f32_e32 v36, v36
	v_rcp_f32_e32 v37, v37
	v_rcp_f32_e32 v38, v38
	v_rcp_f32_e32 v39, v39
	s_nop 0
	v_pk_mul_f32 v[40:41], v[40:41], v[44:45]
	v_pk_mul_f32 v[42:43], v[42:43], v[46:47]
	v_pk_mul_f32 v[32:33], v[32:33], v[36:37]
	v_pk_mul_f32 v[34:35], v[34:35], v[38:39]
	v_cvt_pk_bf16_f32 v44, v40, v41
	v_cvt_pk_bf16_f32 v45, v42, v43
	v_cvt_pk_bf16_f32 v46, v32, v33
	v_cvt_pk_bf16_f32 v47, v34, v35
	global_store_dwordx4 v[170:171], v[44:47], off
	v_fmamk_f32 v166, v161, 0x39800000, v154
	v_rsq_f32_e32 v167, v166
	v_pk_mul_f32 v[24:25], v[28:29], v[24:25]
	v_pk_mul_f32 v[26:27], v[30:31], v[26:27]
	v_pk_mul_f32 v[16:17], v[20:21], v[16:17]
	v_pk_mul_f32 v[18:19], v[22:23], v[18:19]
	v_mul_f32_e32 v168, 0xbfb8aa3b, v167
	v_add_u32_e32 v149, 0xa0, v148
	v_pk_mul_f32 v[28:29], v[28:29], v[168:169] op_sel_hi:[1,0]
	v_pk_mul_f32 v[30:31], v[30:31], v[168:169] op_sel_hi:[1,0]
	v_pk_mul_f32 v[20:21], v[20:21], v[168:169] op_sel_hi:[1,0]
	v_pk_mul_f32 v[22:23], v[22:23], v[168:169] op_sel_hi:[1,0]
	v_exp_f32_e32 v28, v28
	v_exp_f32_e32 v29, v29
	v_exp_f32_e32 v30, v30
	v_exp_f32_e32 v31, v31
	v_exp_f32_e32 v20, v20
	v_exp_f32_e32 v21, v21
	v_exp_f32_e32 v22, v22
	v_exp_f32_e32 v23, v23
	v_mad_i64_i32 v[170:171], s[0:1], v149, s53, v[164:165]
	v_pk_fma_f32 v[28:29], v[28:29], v[166:167], v[166:167] op_sel_hi:[1,0,0]
	v_pk_fma_f32 v[30:31], v[30:31], v[166:167], v[166:167] op_sel_hi:[1,0,0]
	v_pk_fma_f32 v[20:21], v[20:21], v[166:167], v[166:167] op_sel_hi:[1,0,0]
	v_pk_fma_f32 v[22:23], v[22:23], v[166:167], v[166:167] op_sel_hi:[1,0,0]
	v_rcp_f32_e32 v28, v28
	v_rcp_f32_e32 v29, v29
	v_rcp_f32_e32 v30, v30
	v_rcp_f32_e32 v31, v31
	v_rcp_f32_e32 v20, v20
	v_rcp_f32_e32 v21, v21
	v_rcp_f32_e32 v22, v22
	v_rcp_f32_e32 v23, v23
	s_nop 0
	v_pk_mul_f32 v[24:25], v[24:25], v[28:29]
	v_pk_mul_f32 v[26:27], v[26:27], v[30:31]
	v_pk_mul_f32 v[16:17], v[16:17], v[20:21]
	v_pk_mul_f32 v[18:19], v[18:19], v[22:23]
	v_cvt_pk_bf16_f32 v28, v24, v25
	v_cvt_pk_bf16_f32 v29, v26, v27
	v_cvt_pk_bf16_f32 v30, v16, v17
	v_cvt_pk_bf16_f32 v31, v18, v19
	global_store_dwordx4 v[170:171], v[28:31], off
	v_fmamk_f32 v166, v162, 0x39800000, v154
	v_rsq_f32_e32 v167, v166
	v_pk_mul_f32 v[8:9], v[12:13], v[8:9]
	v_pk_mul_f32 v[10:11], v[14:15], v[10:11]
	v_pk_mul_f32 v[0:1], v[4:5], v[0:1]
	v_pk_mul_f32 v[2:3], v[6:7], v[2:3]
	v_mul_f32_e32 v168, 0xbfb8aa3b, v167
	v_add_u32_e32 v149, 0xb0, v148
	v_pk_mul_f32 v[12:13], v[12:13], v[168:169] op_sel_hi:[1,0]
	v_pk_mul_f32 v[14:15], v[14:15], v[168:169] op_sel_hi:[1,0]
	v_pk_mul_f32 v[4:5], v[4:5], v[168:169] op_sel_hi:[1,0]
	v_pk_mul_f32 v[6:7], v[6:7], v[168:169] op_sel_hi:[1,0]
	v_exp_f32_e32 v12, v12
	v_exp_f32_e32 v13, v13
	v_exp_f32_e32 v14, v14
	v_exp_f32_e32 v15, v15
	v_exp_f32_e32 v4, v4
	v_exp_f32_e32 v5, v5
	v_exp_f32_e32 v6, v6
	v_exp_f32_e32 v7, v7
	v_mad_i64_i32 v[170:171], s[0:1], v149, s53, v[164:165]
	v_pk_fma_f32 v[12:13], v[12:13], v[166:167], v[166:167] op_sel_hi:[1,0,0]
	v_pk_fma_f32 v[14:15], v[14:15], v[166:167], v[166:167] op_sel_hi:[1,0,0]
	v_pk_fma_f32 v[4:5], v[4:5], v[166:167], v[166:167] op_sel_hi:[1,0,0]
	v_pk_fma_f32 v[6:7], v[6:7], v[166:167], v[166:167] op_sel_hi:[1,0,0]
	v_rcp_f32_e32 v12, v12
	v_rcp_f32_e32 v13, v13
	v_rcp_f32_e32 v14, v14
	v_rcp_f32_e32 v15, v15
	v_rcp_f32_e32 v4, v4
	v_rcp_f32_e32 v5, v5
	v_rcp_f32_e32 v6, v6
	v_rcp_f32_e32 v7, v7
	s_nop 0
	v_pk_mul_f32 v[8:9], v[8:9], v[12:13]
	v_pk_mul_f32 v[10:11], v[10:11], v[14:15]
	v_pk_mul_f32 v[0:1], v[0:1], v[4:5]
	v_pk_mul_f32 v[2:3], v[2:3], v[6:7]
	s_andn2_b64 vcc, exec, s[4:5]
	s_mov_b64 s[0:1], -1
	v_cvt_pk_bf16_f32 v12, v8, v9
	v_cvt_pk_bf16_f32 v13, v10, v11
	v_cvt_pk_bf16_f32 v14, v0, v1
	v_cvt_pk_bf16_f32 v15, v2, v3
	global_store_dwordx4 v[170:171], v[12:15], off
	s_cbranch_vccnz .LBB0_2822
	s_andn2_b64 vcc, exec, s[12:13]
	s_cbranch_vccnz .LBB0_2821
	s_barrier
	s_branch .LBB0_2821
